# PREP rebalanced: the 64 workgroups that run the two DFT-fold units skip the weight transposes, the other 192 take them
# speedup vs baseline: 1.0146x; 1.0052x over previous
; #define LAS __attribute__((address_space(3)))
; __device__ __forceinline__ void prep_phase(const Params& p, LAS unsigned char* lds, int tid, int mask) {
;     ...
;     const int nfb = G < 64 ? G : 64;
;     if (mask & 4) for (int u = bx - (G - nfb); u >= 0 && u < 128; u += nfb) {
;     ...
;     if (mask & 8) for (int u0 = bx * 4; u0 < 5248; u0 += G * 4) {
;         const float* src[4]; bf16_t* dst[4]; int ldn[4], ldd[4];
; #pragma unroll
;         for (int j = 0; j < 4; ++j) {
;             const int u = u0 + j, l = u / 2624; int r = u % 2624;
;             if (r < 320) { const int kt = r / 20, jj = r % 20, nt = jj < 12 ? jj : jj + 4;
;                 src[j] = p.w_in + (size_t)l * 1024 * 1536 + (size_t)(kt * 64) * 1536 + nt * 64; ldn[j] = 1536;
;                 dst[j] = (bf16_t*)(ws + WS_WIN) + (size_t)l * NIN * 1024 + (size_t)(jj < 12 ? nt * 64 : nt * 64 + 256) * 1024 + kt * 64; ldd[j] = 1024; }
;             else if (r < 576) { r -= 320; const int kt = r / 16, nt = r % 16;
;                 src[j] = p.w_out + (size_t)l * 1024 * 1024 + (size_t)(kt * 64) * 1024 + nt * 64; ldn[j] = 1024;
;                 dst[j] = (bf16_t*)(ws + WS_WOUT) + (size_t)l * 1024 * KOUT + (size_t)(nt * 64) * KOUT + kt * 64; ldd[j] = KOUT; }
;             else if (r < 1600) { r -= 576; const int kt = r / 64, nt = r % 64;
;                 src[j] = p.w1 + (size_t)l * 1024 * 4096 + (size_t)(kt * 64) * 4096 + nt * 64; ldn[j] = 4096;
;                 dst[j] = (bf16_t*)(ws + WS_W1) + (size_t)l * 4096 * 1024 + (size_t)(nt * 64) * 1024 + kt * 64; ldd[j] = 1024; }
;             else { r -= 1600; const int kt = r / 16, nt = r % 16;
;                 src[j] = p.w2 + (size_t)l * 4096 * 1024 + (size_t)(kt * 64) * 1024 + nt * 64; ldn[j] = 1024;
;                 dst[j] = (bf16_t*)(ws + WS_W2) + (size_t)l * 1024 * 4096 + (size_t)(nt * 64) * 4096 + kt * 64; ldd[j] = 4096; }
;         }
;         f32x4 a[4], b[4];
;         {
;             const int r = tid >> 3, cs = (tid & 7) * 8;
; #pragma unroll
;             for (int j = 0; j < 4; ++j) { const f32x4* sp = (const f32x4*)(src[j] + (size_t)r * ldn[j] + cs); a[j] = __builtin_nontemporal_load(sp); b[j] = __builtin_nontemporal_load(sp + 1); }
; #pragma unroll
;             for (int j = 0; j < 4; ++j) {
;                 LAS float* tr = lf + j * (64 * 65) + r * 65 + cs;
.LBB0_65:
	s_add_u32 s59, s88, 0x2200000
	s_addc_u32 s0, s89, 0
	v_writelane_b32 v253, s0, 34
	s_add_u32 s0, s88, 0x1200000
	v_writelane_b32 v253, s0, 35
	s_addc_u32 s0, s89, 0
	v_writelane_b32 v253, s0, 36
	s_add_u32 s0, s88, 0xc00000
	v_writelane_b32 v253, s0, 37
	s_addc_u32 s0, s89, 0
	v_writelane_b32 v253, s0, 38
	s_cmpk_gt_i32 s2, 0xbf
	s_cbranch_scc1 .LBB0_117
	v_and_b32_e32 v8, 56, v16
	s_movk_i32 s0, 0x104
	v_mul_lo_u32 v5, v4, s0
	v_lshlrev_b32_e32 v6, 2, v8
	v_add3_u32 v5, 0, v5, v6
	v_mul_u32_u24_e32 v6, 0x104, v8
	v_lshlrev_b32_e32 v9, 2, v4
	v_mov_b32_e32 v7, 0
	v_add3_u32 v10, 0, v6, v9
	s_lshl_b32 s33, s2, 2
	s_waitcnt lgkmcnt(0)
	s_movk_i32 s48, 0x300
	v_ashrrev_i32_e32 v1, 31, v4
	s_mov_b32 s1, 0
	s_lshl_b32 s49, s2, 8
	s_mov_b32 s50, 0xc000
	s_lshl_b32 s51, s2, 4
	s_movk_i32 s52, 0xc00
	v_lshlrev_b32_e32 v6, 2, v8
	v_add_u32_e32 v11, 0x4100, v5
	v_add_u32_e32 v12, 0x4108, v5
	v_add_u32_e32 v13, 0x4110, v5
	v_add_u32_e32 v14, 0x4118, v5
	v_add_u32_e32 v15, 0x8200, v5
	v_add_u32_e32 v16, 0x8208, v5
	v_add_u32_e32 v17, 0x8210, v5
	v_add_u32_e32 v18, 0x8218, v5
	v_add_u32_e32 v19, 0xc300, v5
	v_add_u32_e32 v20, 0xc308, v5
	v_add_u32_e32 v21, 0xc310, v5
	v_add_u32_e32 v22, 0xc318, v5
	v_lshlrev_b32_e32 v8, 1, v8
	v_mov_b32_e32 v9, v7
	v_add_u32_e32 v23, 0x400, v10
	v_add_u32_e32 v24, 0x4000, v10
	v_add_u32_e32 v25, 0x4200, v10
	v_add_u32_e32 v26, 0x4400, v10
	v_add_u32_e32 v27, 0x4600, v10
	v_add_u32_e32 v28, 0x8000, v10
	v_add_u32_e32 v29, 0x8400, v10
	v_add_u32_e32 v30, 0x8800, v10
	v_add_u32_e32 v31, 0xc200, v10
	v_add_u32_e32 v32, 0xc400, v10
	v_add_u32_e32 v33, 0xc600, v10
	v_add_u32_e32 v34, 0xc800, v10
	s_branch .LBB0_68
